# bf16 packs of each P.V stage spread into the next stage MFMA gaps
# baseline (speedup 1.0000x reference)
; #define ATT_SB() __builtin_amdgcn_sched_barrier(0)
; #define ATT_VRD(arr, ks) do { _Pragma("unroll") for (int cb = 0; cb < NCB; ++cb) { arr[cb][0] = vtr(vbp_ + voff[cb][0] + 4096 * (ks)); arr[cb][1] = vtr(vbp_ + voff[cb][1] + 4096 * (ks)); } } while (0)
; #define ATT_MM(arr, ks) do { _Pragma("unroll") for (int cb = 0; cb < NCB; ++cb) { const bf16x8 vf = {arr[cb][0][0], arr[cb][0][1], arr[cb][0][2], arr[cb][0][3], arr[cb][1][0], arr[cb][1][1], arr[cb][1][2], arr[cb][1][3]}; o[cb] = MFMA32(vf, pf[ks], o[cb]); } } while (0)
; template <bool FOX> ...
;     ...
;         ATT_SB();
;         f32x2v ps2 = {0.f, 0.f};
;         ATT_MM(va, 0); ATT_VRD(va, 1); ATT_EXPCH(s0, 0, pf[0]); ATT_SB();
;         ATT_MM(va, 1); ATT_VRD(va, 2); ATT_EXPCH(s0, 8, pf[1]); ATT_SB();
;         ATT_MM(va, 2); ATT_VRD(va, 3); ATT_EXPCH(s1, 0, pf[2]); ATT_SB();
;         ATT_MM(va, 3); ATT_EXPCH(s1, 8, pf[3]); ATT_SB();
.LBB0_578:
	s_waitcnt lgkmcnt(0)
	v_mfma_f32_32x32x16_bf16 v[80:95], v[18:21], v[148:151], v[80:95]
	v_exp_f32_e32 v128, v128
	v_exp_f32_e32 v129, v129
	v_exp_f32_e32 v130, v130
	ds_read_b64_tr_b16 v[18:19], v17 offset:20480
	ds_read_b64_tr_b16 v[20:21], v31 offset:20480
	v_mfma_f32_32x32x16_bf16 v[64:79], v[22:25], v[148:151], v[64:79]
	v_exp_f32_e32 v131, v131
	v_exp_f32_e32 v132, v132
	v_add_f32_e32 v254, v128, v130
	v_add_f32_e32 v255, v129, v131
	ds_read_b64_tr_b16 v[22:23], v168 offset:20480
	ds_read_b64_tr_b16 v[24:25], v169 offset:20480
	v_mfma_f32_32x32x16_bf16 v[48:63], v[26:29], v[148:151], v[48:63]
	v_exp_f32_e32 v133, v133
	v_exp_f32_e32 v134, v134
	v_add_f32_e32 v254, v254, v132
	v_add_f32_e32 v255, v255, v133
	ds_read_b64_tr_b16 v[26:27], v170 offset:20480
	ds_read_b64_tr_b16 v[28:29], v171 offset:20480
	v_mfma_f32_32x32x16_bf16 v[32:47], v[164:167], v[148:151], v[32:47]
	v_exp_f32_e32 v135, v135
	v_add_f32_e32 v254, v254, v134
	ds_read_b64_tr_b16 v[164:165], v172 offset:20480
	ds_read_b64_tr_b16 v[166:167], v173 offset:20480
	v_add_f32_e32 v255, v255, v135
	s_waitcnt lgkmcnt(0)
	v_mfma_f32_32x32x16_bf16 v[80:95], v[18:21], v[152:155], v[80:95]
	v_exp_f32_e32 v136, v136
	v_exp_f32_e32 v137, v137
	v_exp_f32_e32 v138, v138
	v_cvt_pk_bf16_f32 v148, v128, v129
	ds_read_b64_tr_b16 v[18:19], v17 offset:24576
	ds_read_b64_tr_b16 v[20:21], v31 offset:24576
	v_mfma_f32_32x32x16_bf16 v[64:79], v[22:25], v[152:155], v[64:79]
	v_exp_f32_e32 v139, v139
	v_exp_f32_e32 v140, v140
	v_add_f32_e32 v254, v254, v136
	v_add_f32_e32 v255, v255, v137
	v_cvt_pk_bf16_f32 v149, v130, v131
	ds_read_b64_tr_b16 v[22:23], v168 offset:24576
	ds_read_b64_tr_b16 v[24:25], v169 offset:24576
	v_mfma_f32_32x32x16_bf16 v[48:63], v[26:29], v[152:155], v[48:63]
	v_exp_f32_e32 v141, v141
	v_exp_f32_e32 v142, v142
	v_add_f32_e32 v254, v254, v138
	v_add_f32_e32 v255, v255, v139
	v_cvt_pk_bf16_f32 v150, v132, v133
	ds_read_b64_tr_b16 v[26:27], v170 offset:24576
	ds_read_b64_tr_b16 v[28:29], v171 offset:24576
	v_mfma_f32_32x32x16_bf16 v[32:47], v[164:167], v[152:155], v[32:47]
	v_exp_f32_e32 v143, v143
	v_add_f32_e32 v254, v254, v140
	v_add_f32_e32 v255, v255, v141
	v_cvt_pk_bf16_f32 v151, v134, v135
	ds_read_b64_tr_b16 v[164:165], v172 offset:24576
	ds_read_b64_tr_b16 v[166:167], v173 offset:24576
	v_add_f32_e32 v254, v254, v142
	v_add_f32_e32 v255, v255, v143
	s_waitcnt lgkmcnt(0)
	v_mfma_f32_32x32x16_bf16 v[80:95], v[18:21], v[160:163], v[80:95]
	v_exp_f32_e32 v112, v112
	v_exp_f32_e32 v113, v113
	v_exp_f32_e32 v114, v114
	v_cvt_pk_bf16_f32 v152, v136, v137
	ds_read_b64_tr_b16 v[18:19], v17 offset:28672
	ds_read_b64_tr_b16 v[20:21], v31 offset:28672
	v_mfma_f32_32x32x16_bf16 v[64:79], v[22:25], v[160:163], v[64:79]
	v_exp_f32_e32 v115, v115
	v_exp_f32_e32 v116, v116
	v_add_f32_e32 v254, v254, v112
	v_add_f32_e32 v255, v255, v113
	v_cvt_pk_bf16_f32 v153, v138, v139
	ds_read_b64_tr_b16 v[22:23], v168 offset:28672
	ds_read_b64_tr_b16 v[24:25], v169 offset:28672
	v_mfma_f32_32x32x16_bf16 v[48:63], v[26:29], v[160:163], v[48:63]
	v_exp_f32_e32 v117, v117
	v_exp_f32_e32 v118, v118
	v_add_f32_e32 v254, v254, v114
	v_add_f32_e32 v255, v255, v115
	v_cvt_pk_bf16_f32 v154, v140, v141
	ds_read_b64_tr_b16 v[26:27], v170 offset:28672
	ds_read_b64_tr_b16 v[28:29], v171 offset:28672
	v_mfma_f32_32x32x16_bf16 v[32:47], v[164:167], v[160:163], v[32:47]
	v_exp_f32_e32 v119, v119
	v_add_f32_e32 v254, v254, v116
	v_add_f32_e32 v255, v255, v117
	v_cvt_pk_bf16_f32 v155, v142, v143
	ds_read_b64_tr_b16 v[164:165], v172 offset:28672
	ds_read_b64_tr_b16 v[166:167], v173 offset:28672
	v_add_f32_e32 v254, v254, v118
	v_add_f32_e32 v255, v255, v119
	s_waitcnt lgkmcnt(0)
	s_and_b64 vcc, exec, s[10:11]
	s_cbranch_vccnz .Ldiff_bar0
	s_waitcnt vmcnt(4)
	s_barrier
	s_branch .Ldiff_st3

; #define ATT_SB() __builtin_amdgcn_sched_barrier(0)
; #define ATT_MM(arr, ks) do { _Pragma("unroll") for (int cb = 0; cb < NCB; ++cb) { const bf16x8 vf = {arr[cb][0][0], arr[cb][0][1], arr[cb][0][2], arr[cb][0][3], arr[cb][1][0], arr[cb][1][1], arr[cb][1][2], arr[cb][1][3]}; o[cb] = MFMA32(vf, pf[ks], o[cb]); } } while (0)
; template <bool FOX> ...
;     ...
;         ATT_MM(va, 3); ATT_EXPCH(s1, 8, pf[3]); ATT_SB();
;         lsum += ps2.x + ps2.y;
.Ldiff_st3:
	v_mfma_f32_32x32x16_bf16 v[80:95], v[18:21], v[156:159], v[80:95]
	v_exp_f32_e32 v120, v120
	v_exp_f32_e32 v121, v121
	v_exp_f32_e32 v122, v122
	v_cvt_pk_bf16_f32 v160, v112, v113
	v_mfma_f32_32x32x16_bf16 v[64:79], v[22:25], v[156:159], v[64:79]
	v_exp_f32_e32 v123, v123
	v_exp_f32_e32 v124, v124
	v_add_f32_e32 v254, v254, v120
	v_add_f32_e32 v255, v255, v121
	v_cvt_pk_bf16_f32 v161, v114, v115
	v_mfma_f32_32x32x16_bf16 v[48:63], v[26:29], v[156:159], v[48:63]
	v_exp_f32_e32 v125, v125
	v_exp_f32_e32 v126, v126
	v_add_f32_e32 v254, v254, v122
	v_add_f32_e32 v255, v255, v123
	v_cvt_pk_bf16_f32 v162, v116, v117
	v_mfma_f32_32x32x16_bf16 v[32:47], v[164:167], v[156:159], v[32:47]
	v_exp_f32_e32 v127, v127
	v_add_f32_e32 v254, v254, v124
	v_add_f32_e32 v255, v255, v125
	v_cvt_pk_bf16_f32 v163, v118, v119
	v_add_f32_e32 v254, v254, v126
	v_add_f32_e32 v255, v255, v127
	v_cvt_pk_bf16_f32 v156, v120, v121
	v_cvt_pk_bf16_f32 v157, v122, v123
	v_cvt_pk_bf16_f32 v158, v124, v125
	v_cvt_pk_bf16_f32 v159, v126, v127
	s_andn2_b64 vcc, exec, s[6:7]
	s_cbranch_vccz .LBB0_584
